# 8-phase GEMM tile prologue: first-stage vmcnt(6) wait moved below the accumulator zero-init (v_mov run in the load shadow)
# speedup vs baseline: 1.0074x; 1.0005x over previous
.LBB0_108:
	s_or_b64 exec, exec, s[70:71]
	v_readlane_b32 s4, v254, 9
	s_mov_b64 s[6:7], 0x80
	v_lshl_add_u64 v[4:5], v[0:1], 0, s[6:7]
	v_add_u32_e32 v144, s4, v193
	v_add_u32_e32 v145, 0x2000, v144
	v_readfirstlane_b32 s38, v144
	s_mov_b32 m0, s38
	s_mov_b64 s[4:5], 0x58080
	v_readfirstlane_b32 s38, v145
	s_waitcnt vmcnt(4)
	s_barrier
	global_load_lds_dwordx4 v[4:5], off
	v_lshl_add_u64 v[4:5], v[0:1], 0, s[4:5]
	s_mov_b32 m0, s38
	v_add_u32_e32 v146, 0x8000, v130
	global_load_lds_dwordx4 v[4:5], off
	v_lshl_add_u64 v[4:5], v[2:3], 0, s[6:7]
	v_readfirstlane_b32 s38, v146
	v_lshl_add_u64 v[2:3], v[2:3], 0, s[4:5]
	v_add_u32_e32 v147, 0xa000, v130
	v_readlane_b32 s4, v254, 10
	s_mov_b32 m0, s38
	v_readfirstlane_b32 s38, v147
	v_add_u32_e32 v148, s4, v193
	global_load_lds_dwordx4 v[4:5], off
	s_mov_b32 m0, s38
	s_mov_b64 s[6:7], 0xb0080
	v_readfirstlane_b32 s38, v148
	v_add_u32_e32 v149, 0x2000, v148
	global_load_lds_dwordx4 v[2:3], off
	v_lshl_add_u64 v[2:3], v[0:1], 0, s[6:7]
	s_mov_b32 m0, s38
	s_mov_b64 s[4:5], 0x108080
	v_readfirstlane_b32 s38, v149
	global_load_lds_dwordx4 v[2:3], off
	v_lshl_add_u64 v[0:1], v[0:1], 0, s[4:5]
	s_mov_b32 m0, s38
	s_add_u32 s48, s92, s48
	global_load_lds_dwordx4 v[0:1], off
	s_addc_u32 s49, s93, s49
	s_add_i32 s35, s34, s35
	s_mul_hi_i32 s38, s35, 0x1600
	s_mulk_i32 s35, 0x1600
	s_add_u32 s70, s92, s35
	v_mov_b32_e32 v0, 0
	s_addc_u32 s71, s93, s38
	s_mov_b32 s35, -2
	v_mov_b32_e32 v1, v0
	v_mov_b32_e32 v2, v0
	v_mov_b32_e32 v3, v0
	v_mov_b32_e32 v4, v0
	v_mov_b32_e32 v5, v0
	v_mov_b32_e32 v6, v0
	v_mov_b32_e32 v7, v0
	v_mov_b32_e32 v8, v0
	v_mov_b32_e32 v9, v0
	v_mov_b32_e32 v10, v0
	v_mov_b32_e32 v11, v0
	v_mov_b32_e32 v12, v0
	v_mov_b32_e32 v13, v0
	v_mov_b32_e32 v14, v0
	v_mov_b32_e32 v15, v0
	v_mov_b32_e32 v16, v0
	v_mov_b32_e32 v17, v0
	v_mov_b32_e32 v18, v0
	v_mov_b32_e32 v19, v0
	v_mov_b32_e32 v20, v0
	v_mov_b32_e32 v21, v0
	v_mov_b32_e32 v22, v0
	v_mov_b32_e32 v23, v0
	v_mov_b32_e32 v24, v0
	v_mov_b32_e32 v25, v0
	v_mov_b32_e32 v26, v0
	v_mov_b32_e32 v27, v0
	v_mov_b32_e32 v28, v0
	v_mov_b32_e32 v29, v0
	v_mov_b32_e32 v30, v0
	v_mov_b32_e32 v31, v0
	v_mov_b32_e32 v32, v0
	v_mov_b32_e32 v33, v0
	v_mov_b32_e32 v34, v0
	v_mov_b32_e32 v35, v0
	v_mov_b32_e32 v36, v0
	v_mov_b32_e32 v37, v0
	v_mov_b32_e32 v38, v0
	v_mov_b32_e32 v39, v0
	v_mov_b32_e32 v40, v0
	v_mov_b32_e32 v41, v0
	v_mov_b32_e32 v42, v0
	v_mov_b32_e32 v43, v0
	v_mov_b32_e32 v44, v0
	v_mov_b32_e32 v45, v0
	v_mov_b32_e32 v46, v0
	v_mov_b32_e32 v47, v0
	v_mov_b32_e32 v48, v0
	v_mov_b32_e32 v49, v0
	v_mov_b32_e32 v50, v0
	v_mov_b32_e32 v51, v0
	v_mov_b32_e32 v52, v0
	v_mov_b32_e32 v53, v0
	v_mov_b32_e32 v54, v0
	v_mov_b32_e32 v55, v0
	v_mov_b32_e32 v56, v0
	v_mov_b32_e32 v57, v0
	v_mov_b32_e32 v58, v0
	v_mov_b32_e32 v59, v0
	v_mov_b32_e32 v60, v0
	v_mov_b32_e32 v61, v0
	v_mov_b32_e32 v62, v0
	v_mov_b32_e32 v63, v0
	v_mov_b32_e32 v64, v0
	v_mov_b32_e32 v65, v0
	v_mov_b32_e32 v66, v0
	v_mov_b32_e32 v67, v0
	v_mov_b32_e32 v68, v0
	v_mov_b32_e32 v69, v0
	v_mov_b32_e32 v70, v0
	v_mov_b32_e32 v71, v0
	v_mov_b32_e32 v72, v0
	v_mov_b32_e32 v73, v0
	v_mov_b32_e32 v74, v0
	v_mov_b32_e32 v75, v0
	v_mov_b32_e32 v76, v0
	v_mov_b32_e32 v77, v0
	v_mov_b32_e32 v78, v0
	v_mov_b32_e32 v79, v0
	v_mov_b32_e32 v80, v0
	v_mov_b32_e32 v81, v0
	v_mov_b32_e32 v82, v0
	v_mov_b32_e32 v83, v0
	v_mov_b32_e32 v84, v0
	v_mov_b32_e32 v85, v0
	v_mov_b32_e32 v86, v0
	v_mov_b32_e32 v87, v0
	v_mov_b32_e32 v88, v0
	v_mov_b32_e32 v89, v0
	v_mov_b32_e32 v90, v0
	v_mov_b32_e32 v91, v0
	v_mov_b32_e32 v92, v0
	v_mov_b32_e32 v93, v0
	v_mov_b32_e32 v94, v0
	v_mov_b32_e32 v95, v0
	v_mov_b32_e32 v96, v0
	v_mov_b32_e32 v97, v0
	v_mov_b32_e32 v98, v0
	v_mov_b32_e32 v99, v0
	v_mov_b32_e32 v100, v0
	v_mov_b32_e32 v101, v0
	v_mov_b32_e32 v102, v0
	v_mov_b32_e32 v103, v0
	v_mov_b32_e32 v104, v0
	v_mov_b32_e32 v105, v0
	v_mov_b32_e32 v106, v0
	v_mov_b32_e32 v107, v0
	v_mov_b32_e32 v108, v0
	v_mov_b32_e32 v109, v0
	v_mov_b32_e32 v110, v0
	v_mov_b32_e32 v111, v0
	v_mov_b32_e32 v112, v0
	v_mov_b32_e32 v113, v0
	v_mov_b32_e32 v114, v0
	v_mov_b32_e32 v115, v0
	v_mov_b32_e32 v116, v0
	v_mov_b32_e32 v117, v0
	v_mov_b32_e32 v118, v0
	v_mov_b32_e32 v119, v0
	v_mov_b32_e32 v120, v0
	v_mov_b32_e32 v121, v0
	v_mov_b32_e32 v122, v0
	v_mov_b32_e32 v123, v0
	v_mov_b32_e32 v124, v0
	v_mov_b32_e32 v125, v0
	v_mov_b32_e32 v126, v0
	v_mov_b32_e32 v127, v0
	s_mov_b64 s[8:9], 0x180
	s_waitcnt vmcnt(6)
	s_barrier

.LBB0_281:
	s_or_b64 exec, exec, s[70:71]
	v_readlane_b32 s3, v254, 9
	s_mov_b64 s[4:5], 0x80
	v_lshl_add_u64 v[6:7], v[0:1], 0, s[4:5]
	v_add_u32_e32 v146, s3, v150
	v_add_u32_e32 v147, 0x2000, v146
	v_readfirstlane_b32 s3, v146
	s_mov_b32 m0, s3
	s_mov_b64 s[6:7], 0x20080
	v_readfirstlane_b32 s3, v147
	v_add_u32_e32 v148, 0x8000, v134
	s_waitcnt vmcnt(4)
	s_barrier
	global_load_lds_dwordx4 v[6:7], off
	v_lshl_add_u64 v[0:1], v[0:1], 0, s[6:7]
	s_mov_b32 m0, s3
	v_readfirstlane_b32 s3, v148
	v_add_u32_e32 v149, 0xa000, v134
	global_load_lds_dwordx4 v[0:1], off
	v_lshl_add_u64 v[0:1], v[2:3], 0, s[4:5]
	s_mov_b32 m0, s3
	v_readfirstlane_b32 s3, v149
	global_load_lds_dwordx4 v[0:1], off
	s_mov_b32 m0, s3
	v_readlane_b32 s3, v254, 10
	v_lshl_add_u64 v[0:1], v[2:3], 0, s[6:7]
	global_load_lds_dwordx4 v[0:1], off
	v_add_u32_e32 v161, s3, v150
	v_add_u32_e32 v162, 0x2000, v161
	v_readfirstlane_b32 s3, v161
	v_lshl_add_u64 v[0:1], v[4:5], 0, s[4:5]
	s_mov_b32 m0, s3
	v_readfirstlane_b32 s3, v162
	global_load_lds_dwordx4 v[0:1], off
	v_lshl_add_u64 v[0:1], v[4:5], 0, s[6:7]
	s_mov_b32 m0, s3
	s_add_u32 s48, s92, s48
	global_load_lds_dwordx4 v[0:1], off
	s_addc_u32 s49, s93, s49
	s_add_i32 s34, s22, s23
	s_ashr_i32 s35, s34, 31
	s_lshl_b64 s[34:35], s[34:35], 11
	s_add_u32 s70, s92, s34
	v_mov_b32_e32 v0, 0
	s_addc_u32 s71, s93, s35
	s_mov_b32 s3, -2
	v_mov_b32_e32 v1, v0
	v_mov_b32_e32 v2, v0
	v_mov_b32_e32 v3, v0
	v_mov_b32_e32 v4, v0
	v_mov_b32_e32 v5, v0
	v_mov_b32_e32 v6, v0
	v_mov_b32_e32 v7, v0
	v_mov_b32_e32 v8, v0
	v_mov_b32_e32 v9, v0
	v_mov_b32_e32 v10, v0
	v_mov_b32_e32 v11, v0
	v_mov_b32_e32 v12, v0
	v_mov_b32_e32 v13, v0
	v_mov_b32_e32 v14, v0
	v_mov_b32_e32 v15, v0
	v_mov_b32_e32 v16, v0
	v_mov_b32_e32 v17, v0
	v_mov_b32_e32 v18, v0
	v_mov_b32_e32 v19, v0
	v_mov_b32_e32 v20, v0
	v_mov_b32_e32 v21, v0
	v_mov_b32_e32 v22, v0
	v_mov_b32_e32 v23, v0
	v_mov_b32_e32 v24, v0
	v_mov_b32_e32 v25, v0
	v_mov_b32_e32 v26, v0
	v_mov_b32_e32 v27, v0
	v_mov_b32_e32 v28, v0
	v_mov_b32_e32 v29, v0
	v_mov_b32_e32 v30, v0
	v_mov_b32_e32 v31, v0
	v_mov_b32_e32 v32, v0
	v_mov_b32_e32 v33, v0
	v_mov_b32_e32 v34, v0
	v_mov_b32_e32 v35, v0
	v_mov_b32_e32 v36, v0
	v_mov_b32_e32 v37, v0
	v_mov_b32_e32 v38, v0
	v_mov_b32_e32 v39, v0
	v_mov_b32_e32 v40, v0
	v_mov_b32_e32 v41, v0
	v_mov_b32_e32 v42, v0
	v_mov_b32_e32 v43, v0
	v_mov_b32_e32 v44, v0
	v_mov_b32_e32 v45, v0
	v_mov_b32_e32 v46, v0
	v_mov_b32_e32 v47, v0
	v_mov_b32_e32 v48, v0
	v_mov_b32_e32 v49, v0
	v_mov_b32_e32 v50, v0
	v_mov_b32_e32 v51, v0
	v_mov_b32_e32 v52, v0
	v_mov_b32_e32 v53, v0
	v_mov_b32_e32 v54, v0
	v_mov_b32_e32 v55, v0
	v_mov_b32_e32 v56, v0
	v_mov_b32_e32 v57, v0
	v_mov_b32_e32 v58, v0
	v_mov_b32_e32 v59, v0
	v_mov_b32_e32 v60, v0
	v_mov_b32_e32 v61, v0
	v_mov_b32_e32 v62, v0
	v_mov_b32_e32 v63, v0
	v_mov_b32_e32 v64, v0
	v_mov_b32_e32 v65, v0
	v_mov_b32_e32 v66, v0
	v_mov_b32_e32 v67, v0
	v_mov_b32_e32 v68, v0
	v_mov_b32_e32 v69, v0
	v_mov_b32_e32 v70, v0
	v_mov_b32_e32 v71, v0
	v_mov_b32_e32 v72, v0
	v_mov_b32_e32 v73, v0
	v_mov_b32_e32 v74, v0
	v_mov_b32_e32 v75, v0
	v_mov_b32_e32 v76, v0
	v_mov_b32_e32 v77, v0
	v_mov_b32_e32 v78, v0
	v_mov_b32_e32 v79, v0
	v_mov_b32_e32 v80, v0
	v_mov_b32_e32 v81, v0
	v_mov_b32_e32 v82, v0
	v_mov_b32_e32 v83, v0
	v_mov_b32_e32 v84, v0
	v_mov_b32_e32 v85, v0
	v_mov_b32_e32 v86, v0
	v_mov_b32_e32 v87, v0
	v_mov_b32_e32 v88, v0
	v_mov_b32_e32 v89, v0
	v_mov_b32_e32 v90, v0
	v_mov_b32_e32 v91, v0
	v_mov_b32_e32 v92, v0
	v_mov_b32_e32 v93, v0
	v_mov_b32_e32 v94, v0
	v_mov_b32_e32 v95, v0
	v_mov_b32_e32 v96, v0
	v_mov_b32_e32 v97, v0
	v_mov_b32_e32 v98, v0
	v_mov_b32_e32 v99, v0
	v_mov_b32_e32 v100, v0
	v_mov_b32_e32 v101, v0
	v_mov_b32_e32 v102, v0
	v_mov_b32_e32 v103, v0
	v_mov_b32_e32 v104, v0
	v_mov_b32_e32 v105, v0
	v_mov_b32_e32 v106, v0
	v_mov_b32_e32 v107, v0
	v_mov_b32_e32 v108, v0
	v_mov_b32_e32 v109, v0
	v_mov_b32_e32 v110, v0
	v_mov_b32_e32 v111, v0
	v_mov_b32_e32 v112, v0
	v_mov_b32_e32 v113, v0
	v_mov_b32_e32 v114, v0
	v_mov_b32_e32 v115, v0
	v_mov_b32_e32 v116, v0
	v_mov_b32_e32 v117, v0
	v_mov_b32_e32 v118, v0
	v_mov_b32_e32 v119, v0
	v_mov_b32_e32 v120, v0
	v_mov_b32_e32 v121, v0
	v_mov_b32_e32 v122, v0
	v_mov_b32_e32 v123, v0
	v_mov_b32_e32 v124, v0
	v_mov_b32_e32 v125, v0
	v_mov_b32_e32 v126, v0
	v_mov_b32_e32 v127, v0
	s_mov_b64 s[4:5], 0x8440080
	s_mov_b64 s[6:7], 0x8460080
	s_mov_b64 s[8:9], 0x8400100
	s_mov_b64 s[10:11], 0x8420100
	s_mov_b64 s[34:35], 0x8440100
	s_mov_b64 s[38:39], 0x149c0100
	s_mov_b64 s[76:77], 0x149e0100
	s_mov_b64 s[78:79], 0x14a00100
	s_mov_b64 s[80:81], 0x14a20100
	s_mov_b64 s[82:83], 0x149c0180
	s_mov_b64 s[90:91], 0x149e0180
	s_mov_b64 s[16:17], 0x14a00180
	s_mov_b64 s[18:19], 0x14a20180
	s_mov_b64 s[46:47], 0x8460100
	s_mov_b64 s[50:51], 0x8400180
	s_waitcnt vmcnt(6)
	s_barrier

.LBB0_323:
	s_or_b64 exec, exec, s[48:49]
	v_readlane_b32 s1, v254, 9
	s_mov_b64 s[4:5], 0x80
	v_lshl_add_u64 v[6:7], v[0:1], 0, s[4:5]
	v_add_u32_e32 v157, s1, v142
	v_add_u32_e32 v158, 0x2000, v157
	v_readfirstlane_b32 s1, v157
	s_mov_b32 m0, s1
	s_mov_b64 s[6:7], 0x20080
	v_readfirstlane_b32 s1, v158
	v_add_u32_e32 v159, 0x8000, v134
	s_waitcnt vmcnt(4)
	s_barrier
	global_load_lds_dwordx4 v[6:7], off
	v_lshl_add_u64 v[0:1], v[0:1], 0, s[6:7]
	s_mov_b32 m0, s1
	v_readfirstlane_b32 s1, v159
	v_add_u32_e32 v160, 0xa000, v134
	global_load_lds_dwordx4 v[0:1], off
	v_lshl_add_u64 v[0:1], v[2:3], 0, s[4:5]
	s_mov_b32 m0, s1
	v_readfirstlane_b32 s1, v160
	global_load_lds_dwordx4 v[0:1], off
	s_mov_b32 m0, s1
	v_readlane_b32 s1, v254, 10
	v_lshl_add_u64 v[0:1], v[2:3], 0, s[6:7]
	global_load_lds_dwordx4 v[0:1], off
	v_add_u32_e32 v161, s1, v142
	v_add_u32_e32 v162, 0x2000, v161
	v_readfirstlane_b32 s1, v161
	v_lshl_add_u64 v[0:1], v[4:5], 0, s[4:5]
	s_mov_b32 m0, s1
	v_readfirstlane_b32 s1, v162
	global_load_lds_dwordx4 v[0:1], off
	v_lshl_add_u64 v[0:1], v[4:5], 0, s[6:7]
	s_mov_b32 m0, s1
	s_add_u32 s44, s92, s44
	global_load_lds_dwordx4 v[0:1], off
	s_addc_u32 s45, s93, s45
	s_add_i32 s22, s23, s22
	s_ashr_i32 s23, s22, 31
	s_lshl_b64 s[22:23], s[22:23], 11
	s_add_u32 s48, s92, s22
	v_mov_b32_e32 v0, 0
	s_addc_u32 s49, s93, s23
	s_mov_b32 s1, -2
	v_mov_b32_e32 v1, v0
	v_mov_b32_e32 v2, v0
	v_mov_b32_e32 v3, v0
	v_mov_b32_e32 v4, v0
	v_mov_b32_e32 v5, v0
	v_mov_b32_e32 v6, v0
	v_mov_b32_e32 v7, v0
	v_mov_b32_e32 v8, v0
	v_mov_b32_e32 v9, v0
	v_mov_b32_e32 v10, v0
	v_mov_b32_e32 v11, v0
	v_mov_b32_e32 v12, v0
	v_mov_b32_e32 v13, v0
	v_mov_b32_e32 v14, v0
	v_mov_b32_e32 v15, v0
	v_mov_b32_e32 v16, v0
	v_mov_b32_e32 v17, v0
	v_mov_b32_e32 v18, v0
	v_mov_b32_e32 v19, v0
	v_mov_b32_e32 v20, v0
	v_mov_b32_e32 v21, v0
	v_mov_b32_e32 v22, v0
	v_mov_b32_e32 v23, v0
	v_mov_b32_e32 v24, v0
	v_mov_b32_e32 v25, v0
	v_mov_b32_e32 v26, v0
	v_mov_b32_e32 v27, v0
	v_mov_b32_e32 v28, v0
	v_mov_b32_e32 v29, v0
	v_mov_b32_e32 v30, v0
	v_mov_b32_e32 v31, v0
	v_mov_b32_e32 v32, v0
	v_mov_b32_e32 v33, v0
	v_mov_b32_e32 v34, v0
	v_mov_b32_e32 v35, v0
	v_mov_b32_e32 v36, v0
	v_mov_b32_e32 v37, v0
	v_mov_b32_e32 v38, v0
	v_mov_b32_e32 v39, v0
	v_mov_b32_e32 v40, v0
	v_mov_b32_e32 v41, v0
	v_mov_b32_e32 v42, v0
	v_mov_b32_e32 v43, v0
	v_mov_b32_e32 v44, v0
	v_mov_b32_e32 v45, v0
	v_mov_b32_e32 v46, v0
	v_mov_b32_e32 v47, v0
	v_mov_b32_e32 v48, v0
	v_mov_b32_e32 v49, v0
	v_mov_b32_e32 v50, v0
	v_mov_b32_e32 v51, v0
	v_mov_b32_e32 v52, v0
	v_mov_b32_e32 v53, v0
	v_mov_b32_e32 v54, v0
	v_mov_b32_e32 v55, v0
	v_mov_b32_e32 v56, v0
	v_mov_b32_e32 v57, v0
	v_mov_b32_e32 v58, v0
	v_mov_b32_e32 v59, v0
	v_mov_b32_e32 v60, v0
	v_mov_b32_e32 v61, v0
	v_mov_b32_e32 v62, v0
	v_mov_b32_e32 v63, v0
	v_mov_b32_e32 v64, v0
	v_mov_b32_e32 v65, v0
	v_mov_b32_e32 v66, v0
	v_mov_b32_e32 v67, v0
	v_mov_b32_e32 v68, v0
	v_mov_b32_e32 v69, v0
	v_mov_b32_e32 v70, v0
	v_mov_b32_e32 v71, v0
	v_mov_b32_e32 v72, v0
	v_mov_b32_e32 v73, v0
	v_mov_b32_e32 v74, v0
	v_mov_b32_e32 v75, v0
	v_mov_b32_e32 v76, v0
	v_mov_b32_e32 v77, v0
	v_mov_b32_e32 v78, v0
	v_mov_b32_e32 v79, v0
	v_mov_b32_e32 v80, v0
	v_mov_b32_e32 v81, v0
	v_mov_b32_e32 v82, v0
	v_mov_b32_e32 v83, v0
	v_mov_b32_e32 v84, v0
	v_mov_b32_e32 v85, v0
	v_mov_b32_e32 v86, v0
	v_mov_b32_e32 v87, v0
	v_mov_b32_e32 v88, v0
	v_mov_b32_e32 v89, v0
	v_mov_b32_e32 v90, v0
	v_mov_b32_e32 v91, v0
	v_mov_b32_e32 v92, v0
	v_mov_b32_e32 v93, v0
	v_mov_b32_e32 v94, v0
	v_mov_b32_e32 v95, v0
	v_mov_b32_e32 v96, v0
	v_mov_b32_e32 v97, v0
	v_mov_b32_e32 v98, v0
	v_mov_b32_e32 v99, v0
	v_mov_b32_e32 v100, v0
	v_mov_b32_e32 v101, v0
	v_mov_b32_e32 v102, v0
	v_mov_b32_e32 v103, v0
	v_mov_b32_e32 v104, v0
	v_mov_b32_e32 v105, v0
	v_mov_b32_e32 v106, v0
	v_mov_b32_e32 v107, v0
	v_mov_b32_e32 v108, v0
	v_mov_b32_e32 v109, v0
	v_mov_b32_e32 v110, v0
	v_mov_b32_e32 v111, v0
	v_mov_b32_e32 v112, v0
	v_mov_b32_e32 v113, v0
	v_mov_b32_e32 v114, v0
	v_mov_b32_e32 v115, v0
	v_mov_b32_e32 v116, v0
	v_mov_b32_e32 v117, v0
	v_mov_b32_e32 v118, v0
	v_mov_b32_e32 v119, v0
	v_mov_b32_e32 v120, v0
	v_mov_b32_e32 v121, v0
	v_mov_b32_e32 v122, v0
	v_mov_b32_e32 v123, v0
	v_mov_b32_e32 v124, v0
	v_mov_b32_e32 v125, v0
	v_mov_b32_e32 v126, v0
	v_mov_b32_e32 v127, v0
	s_mov_b64 s[4:5], 0x8440080
	s_mov_b64 s[6:7], 0x8460080
	s_mov_b64 s[8:9], 0x8400100
	s_mov_b64 s[10:11], 0x8420100
	s_mov_b64 s[14:15], 0x8440100
	s_mov_b64 s[12:13], 0x14420100
	s_mov_b64 s[16:17], 0x14440100
	s_mov_b64 s[18:19], 0x14460100
	s_mov_b64 s[22:23], 0x14480100
	s_mov_b64 s[34:35], 0x14420180
	s_mov_b64 s[38:39], 0x14440180
	s_mov_b64 s[72:73], 0x14460180
	s_mov_b64 s[76:77], 0x14480180
	s_mov_b64 s[46:47], 0x8460100
	s_mov_b64 s[50:51], 0x8400180
	s_waitcnt vmcnt(6)
	s_barrier

.LBB0_339:
	s_or_b64 exec, exec, s[70:71]
	v_readlane_b32 s3, v254, 9
	s_mov_b64 s[4:5], 0x80
	v_lshl_add_u64 v[6:7], v[0:1], 0, s[4:5]
	v_add_u32_e32 v146, s3, v150
	v_add_u32_e32 v147, 0x2000, v146
	v_readfirstlane_b32 s3, v146
	s_mov_b32 m0, s3
	s_mov_b64 s[6:7], 0x20080
	v_readfirstlane_b32 s3, v147
	v_add_u32_e32 v148, 0x8000, v134
	s_waitcnt vmcnt(4)
	s_barrier
	global_load_lds_dwordx4 v[6:7], off
	v_lshl_add_u64 v[0:1], v[0:1], 0, s[6:7]
	s_mov_b32 m0, s3
	v_readfirstlane_b32 s3, v148
	v_add_u32_e32 v149, 0xa000, v134
	global_load_lds_dwordx4 v[0:1], off
	v_lshl_add_u64 v[0:1], v[2:3], 0, s[4:5]
	s_mov_b32 m0, s3
	v_readfirstlane_b32 s3, v149
	global_load_lds_dwordx4 v[0:1], off
	s_mov_b32 m0, s3
	v_readlane_b32 s3, v254, 10
	v_lshl_add_u64 v[0:1], v[2:3], 0, s[6:7]
	global_load_lds_dwordx4 v[0:1], off
	v_add_u32_e32 v161, s3, v150
	v_add_u32_e32 v162, 0x2000, v161
	v_readfirstlane_b32 s3, v161
	v_lshl_add_u64 v[0:1], v[4:5], 0, s[4:5]
	s_mov_b32 m0, s3
	v_readfirstlane_b32 s3, v162
	global_load_lds_dwordx4 v[0:1], off
	v_lshl_add_u64 v[0:1], v[4:5], 0, s[6:7]
	s_mov_b32 m0, s3
	s_add_u32 s48, s92, s48
	global_load_lds_dwordx4 v[0:1], off
	s_addc_u32 s49, s93, s49
	s_add_i32 s34, s22, s23
	s_ashr_i32 s35, s34, 31
	s_lshl_b64 s[34:35], s[34:35], 11
	s_add_u32 s70, s92, s34
	v_mov_b32_e32 v0, 0
	s_addc_u32 s71, s93, s35
	s_mov_b32 s3, -2
	v_mov_b32_e32 v1, v0
	v_mov_b32_e32 v2, v0
	v_mov_b32_e32 v3, v0
	v_mov_b32_e32 v4, v0
	v_mov_b32_e32 v5, v0
	v_mov_b32_e32 v6, v0
	v_mov_b32_e32 v7, v0
	v_mov_b32_e32 v8, v0
	v_mov_b32_e32 v9, v0
	v_mov_b32_e32 v10, v0
	v_mov_b32_e32 v11, v0
	v_mov_b32_e32 v12, v0
	v_mov_b32_e32 v13, v0
	v_mov_b32_e32 v14, v0
	v_mov_b32_e32 v15, v0
	v_mov_b32_e32 v16, v0
	v_mov_b32_e32 v17, v0
	v_mov_b32_e32 v18, v0
	v_mov_b32_e32 v19, v0
	v_mov_b32_e32 v20, v0
	v_mov_b32_e32 v21, v0
	v_mov_b32_e32 v22, v0
	v_mov_b32_e32 v23, v0
	v_mov_b32_e32 v24, v0
	v_mov_b32_e32 v25, v0
	v_mov_b32_e32 v26, v0
	v_mov_b32_e32 v27, v0
	v_mov_b32_e32 v28, v0
	v_mov_b32_e32 v29, v0
	v_mov_b32_e32 v30, v0
	v_mov_b32_e32 v31, v0
	v_mov_b32_e32 v32, v0
	v_mov_b32_e32 v33, v0
	v_mov_b32_e32 v34, v0
	v_mov_b32_e32 v35, v0
	v_mov_b32_e32 v36, v0
	v_mov_b32_e32 v37, v0
	v_mov_b32_e32 v38, v0
	v_mov_b32_e32 v39, v0
	v_mov_b32_e32 v40, v0
	v_mov_b32_e32 v41, v0
	v_mov_b32_e32 v42, v0
	v_mov_b32_e32 v43, v0
	v_mov_b32_e32 v44, v0
	v_mov_b32_e32 v45, v0
	v_mov_b32_e32 v46, v0
	v_mov_b32_e32 v47, v0
	v_mov_b32_e32 v48, v0
	v_mov_b32_e32 v49, v0
	v_mov_b32_e32 v50, v0
	v_mov_b32_e32 v51, v0
	v_mov_b32_e32 v52, v0
	v_mov_b32_e32 v53, v0
	v_mov_b32_e32 v54, v0
	v_mov_b32_e32 v55, v0
	v_mov_b32_e32 v56, v0
	v_mov_b32_e32 v57, v0
	v_mov_b32_e32 v58, v0
	v_mov_b32_e32 v59, v0
	v_mov_b32_e32 v60, v0
	v_mov_b32_e32 v61, v0
	v_mov_b32_e32 v62, v0
	v_mov_b32_e32 v63, v0
	v_mov_b32_e32 v64, v0
	v_mov_b32_e32 v65, v0
	v_mov_b32_e32 v66, v0
	v_mov_b32_e32 v67, v0
	v_mov_b32_e32 v68, v0
	v_mov_b32_e32 v69, v0
	v_mov_b32_e32 v70, v0
	v_mov_b32_e32 v71, v0
	v_mov_b32_e32 v72, v0
	v_mov_b32_e32 v73, v0
	v_mov_b32_e32 v74, v0
	v_mov_b32_e32 v75, v0
	v_mov_b32_e32 v76, v0
	v_mov_b32_e32 v77, v0
	v_mov_b32_e32 v78, v0
	v_mov_b32_e32 v79, v0
	v_mov_b32_e32 v80, v0
	v_mov_b32_e32 v81, v0
	v_mov_b32_e32 v82, v0
	v_mov_b32_e32 v83, v0
	v_mov_b32_e32 v84, v0
	v_mov_b32_e32 v85, v0
	v_mov_b32_e32 v86, v0
	v_mov_b32_e32 v87, v0
	v_mov_b32_e32 v88, v0
	v_mov_b32_e32 v89, v0
	v_mov_b32_e32 v90, v0
	v_mov_b32_e32 v91, v0
	v_mov_b32_e32 v92, v0
	v_mov_b32_e32 v93, v0
	v_mov_b32_e32 v94, v0
	v_mov_b32_e32 v95, v0
	v_mov_b32_e32 v96, v0
	v_mov_b32_e32 v97, v0
	v_mov_b32_e32 v98, v0
	v_mov_b32_e32 v99, v0
	v_mov_b32_e32 v100, v0
	v_mov_b32_e32 v101, v0
	v_mov_b32_e32 v102, v0
	v_mov_b32_e32 v103, v0
	v_mov_b32_e32 v104, v0
	v_mov_b32_e32 v105, v0
	v_mov_b32_e32 v106, v0
	v_mov_b32_e32 v107, v0
	v_mov_b32_e32 v108, v0
	v_mov_b32_e32 v109, v0
	v_mov_b32_e32 v110, v0
	v_mov_b32_e32 v111, v0
	v_mov_b32_e32 v112, v0
	v_mov_b32_e32 v113, v0
	v_mov_b32_e32 v114, v0
	v_mov_b32_e32 v115, v0
	v_mov_b32_e32 v116, v0
	v_mov_b32_e32 v117, v0
	v_mov_b32_e32 v118, v0
	v_mov_b32_e32 v119, v0
	v_mov_b32_e32 v120, v0
	v_mov_b32_e32 v121, v0
	v_mov_b32_e32 v122, v0
	v_mov_b32_e32 v123, v0
	v_mov_b32_e32 v124, v0
	v_mov_b32_e32 v125, v0
	v_mov_b32_e32 v126, v0
	v_mov_b32_e32 v127, v0
	s_mov_b64 s[4:5], 0x149c0100
	s_mov_b64 s[6:7], 0x149e0100
	s_mov_b64 s[34:35], 0x14a00100
	s_mov_b64 s[76:77], 0x14a20100
	s_mov_b64 s[78:79], 0x149c0180
	s_mov_b64 s[80:81], 0x149e0180
	s_mov_b64 s[82:83], 0x14a00180
	s_mov_b64 s[16:17], 0x14a20180
	s_waitcnt vmcnt(6)
	s_barrier

.LBB0_1050:
	s_or_b64 exec, exec, s[48:49]
	v_readlane_b32 s1, v254, 9
	s_mov_b64 s[4:5], 0x80
	v_lshl_add_u64 v[6:7], v[0:1], 0, s[4:5]
	v_add_u32_e32 v157, s1, v132
	v_add_u32_e32 v158, 0x2000, v157
	v_readfirstlane_b32 s1, v157
	s_mov_b32 m0, s1
	s_mov_b64 s[6:7], 0x20080
	v_readfirstlane_b32 s1, v158
	v_add_u32_e32 v159, 0x8000, v151
	s_waitcnt vmcnt(4)
	s_barrier
	global_load_lds_dwordx4 v[6:7], off
	v_lshl_add_u64 v[0:1], v[0:1], 0, s[6:7]
	s_mov_b32 m0, s1
	v_readfirstlane_b32 s1, v159
	v_add_u32_e32 v160, 0xa000, v151
	global_load_lds_dwordx4 v[0:1], off
	v_lshl_add_u64 v[0:1], v[2:3], 0, s[4:5]
	s_mov_b32 m0, s1
	v_readfirstlane_b32 s1, v160
	global_load_lds_dwordx4 v[0:1], off
	s_mov_b32 m0, s1
	v_readlane_b32 s1, v254, 10
	v_lshl_add_u64 v[0:1], v[2:3], 0, s[6:7]
	global_load_lds_dwordx4 v[0:1], off
	v_add_u32_e32 v161, s1, v132
	v_add_u32_e32 v162, 0x2000, v161
	v_readfirstlane_b32 s1, v161
	v_lshl_add_u64 v[0:1], v[4:5], 0, s[4:5]
	s_mov_b32 m0, s1
	v_readfirstlane_b32 s1, v162
	global_load_lds_dwordx4 v[0:1], off
	v_lshl_add_u64 v[0:1], v[4:5], 0, s[6:7]
	s_mov_b32 m0, s1
	s_add_u32 s44, s92, s44
	global_load_lds_dwordx4 v[0:1], off
	s_addc_u32 s45, s93, s45
	s_add_i32 s34, s35, s34
	s_ashr_i32 s35, s34, 31
	s_lshl_b64 s[34:35], s[34:35], 11
	s_add_u32 s48, s92, s34
	v_mov_b32_e32 v0, 0
	s_addc_u32 s49, s93, s35
	s_mov_b32 s1, -2
	v_mov_b32_e32 v1, v0
	v_mov_b32_e32 v2, v0
	v_mov_b32_e32 v3, v0
	v_mov_b32_e32 v4, v0
	v_mov_b32_e32 v5, v0
	v_mov_b32_e32 v6, v0
	v_mov_b32_e32 v7, v0
	v_mov_b32_e32 v8, v0
	v_mov_b32_e32 v9, v0
	v_mov_b32_e32 v10, v0
	v_mov_b32_e32 v11, v0
	v_mov_b32_e32 v12, v0
	v_mov_b32_e32 v13, v0
	v_mov_b32_e32 v14, v0
	v_mov_b32_e32 v15, v0
	v_mov_b32_e32 v16, v0
	v_mov_b32_e32 v17, v0
	v_mov_b32_e32 v18, v0
	v_mov_b32_e32 v19, v0
	v_mov_b32_e32 v20, v0
	v_mov_b32_e32 v21, v0
	v_mov_b32_e32 v22, v0
	v_mov_b32_e32 v23, v0
	v_mov_b32_e32 v24, v0
	v_mov_b32_e32 v25, v0
	v_mov_b32_e32 v26, v0
	v_mov_b32_e32 v27, v0
	v_mov_b32_e32 v28, v0
	v_mov_b32_e32 v29, v0
	v_mov_b32_e32 v30, v0
	v_mov_b32_e32 v31, v0
	v_mov_b32_e32 v32, v0
	v_mov_b32_e32 v33, v0
	v_mov_b32_e32 v34, v0
	v_mov_b32_e32 v35, v0
	v_mov_b32_e32 v36, v0
	v_mov_b32_e32 v37, v0
	v_mov_b32_e32 v38, v0
	v_mov_b32_e32 v39, v0
	v_mov_b32_e32 v40, v0
	v_mov_b32_e32 v41, v0
	v_mov_b32_e32 v42, v0
	v_mov_b32_e32 v43, v0
	v_mov_b32_e32 v44, v0
	v_mov_b32_e32 v45, v0
	v_mov_b32_e32 v46, v0
	v_mov_b32_e32 v47, v0
	v_mov_b32_e32 v48, v0
	v_mov_b32_e32 v49, v0
	v_mov_b32_e32 v50, v0
	v_mov_b32_e32 v51, v0
	v_mov_b32_e32 v52, v0
	v_mov_b32_e32 v53, v0
	v_mov_b32_e32 v54, v0
	v_mov_b32_e32 v55, v0
	v_mov_b32_e32 v56, v0
	v_mov_b32_e32 v57, v0
	v_mov_b32_e32 v58, v0
	v_mov_b32_e32 v59, v0
	v_mov_b32_e32 v60, v0
	v_mov_b32_e32 v61, v0
	v_mov_b32_e32 v62, v0
	v_mov_b32_e32 v63, v0
	v_mov_b32_e32 v64, v0
	v_mov_b32_e32 v65, v0
	v_mov_b32_e32 v66, v0
	v_mov_b32_e32 v67, v0
	v_mov_b32_e32 v68, v0
	v_mov_b32_e32 v69, v0
	v_mov_b32_e32 v70, v0
	v_mov_b32_e32 v71, v0
	v_mov_b32_e32 v72, v0
	v_mov_b32_e32 v73, v0
	v_mov_b32_e32 v74, v0
	v_mov_b32_e32 v75, v0
	v_mov_b32_e32 v76, v0
	v_mov_b32_e32 v77, v0
	v_mov_b32_e32 v78, v0
	v_mov_b32_e32 v79, v0
	v_mov_b32_e32 v80, v0
	v_mov_b32_e32 v81, v0
	v_mov_b32_e32 v82, v0
	v_mov_b32_e32 v83, v0
	v_mov_b32_e32 v84, v0
	v_mov_b32_e32 v85, v0
	v_mov_b32_e32 v86, v0
	v_mov_b32_e32 v87, v0
	v_mov_b32_e32 v88, v0
	v_mov_b32_e32 v89, v0
	v_mov_b32_e32 v90, v0
	v_mov_b32_e32 v91, v0
	v_mov_b32_e32 v92, v0
	v_mov_b32_e32 v93, v0
	v_mov_b32_e32 v94, v0
	v_mov_b32_e32 v95, v0
	v_mov_b32_e32 v96, v0
	v_mov_b32_e32 v97, v0
	v_mov_b32_e32 v98, v0
	v_mov_b32_e32 v99, v0
	v_mov_b32_e32 v100, v0
	v_mov_b32_e32 v101, v0
	v_mov_b32_e32 v102, v0
	v_mov_b32_e32 v103, v0
	v_mov_b32_e32 v104, v0
	v_mov_b32_e32 v105, v0
	v_mov_b32_e32 v106, v0
	v_mov_b32_e32 v107, v0
	v_mov_b32_e32 v108, v0
	v_mov_b32_e32 v109, v0
	v_mov_b32_e32 v110, v0
	v_mov_b32_e32 v111, v0
	v_mov_b32_e32 v112, v0
	v_mov_b32_e32 v113, v0
	v_mov_b32_e32 v114, v0
	v_mov_b32_e32 v115, v0
	v_mov_b32_e32 v116, v0
	v_mov_b32_e32 v117, v0
	v_mov_b32_e32 v118, v0
	v_mov_b32_e32 v119, v0
	v_mov_b32_e32 v120, v0
	v_mov_b32_e32 v121, v0
	v_mov_b32_e32 v122, v0
	v_mov_b32_e32 v123, v0
	v_mov_b32_e32 v124, v0
	v_mov_b32_e32 v125, v0
	v_mov_b32_e32 v126, v0
	v_mov_b32_e32 v127, v0
	s_mov_b64 s[4:5], 0x8440080
	s_mov_b64 s[6:7], 0x8460080
	s_mov_b64 s[8:9], 0x8400100
	s_mov_b64 s[10:11], 0x8420100
	s_mov_b64 s[14:15], 0x8440100
	s_mov_b64 s[12:13], 0x14420100
	s_mov_b64 s[16:17], 0x14440100
	s_mov_b64 s[18:19], 0x14460100
	s_mov_b64 s[34:35], 0x14480100
	s_mov_b64 s[38:39], 0x14420180
	s_mov_b64 s[70:71], 0x14440180
	s_mov_b64 s[72:73], 0x14460180
	s_mov_b64 s[74:75], 0x14480180
	s_mov_b64 s[46:47], 0x8460100
	s_mov_b64 s[50:51], 0x8400180
	s_waitcnt vmcnt(6)
	s_barrier
